# post_rows: next row's loads issued during the current row's reduction/normalisation chain (cross-iteration prefetch)
# speedup vs baseline: 1.0072x; 1.0024x over previous
; __device__ __forceinline__ float fexp2(float x) { return __builtin_amdgcn_exp2f(x); }
; __device__ __forceinline__ float frcp(float x) { return __builtin_amdgcn_rcpf(x); }
; __device__ __forceinline__ void post_rows(const bf16_t* OP, const float* LSE, const bf16_t* zC, bf16_t* yb, bf16_t* yc, const float* hnorm, int tid, int bid, int nbk) {
;     const int lane = tid & 63, wv = tid >> 6;
;     const int gw = bid * 8 + wv, NGW = nbk * 8;
;     for (int r = gw; r < MH; r += NGW) {
;         {
;             const int hb = lane >> 3;
;             const float l0 = LSE[((size_t)0 * MH + r) * 8 + hb], l1 = LSE[((size_t)1 * MH + r) * 8 + hb], l2 = LSE[((size_t)2 * MH + r) * 8 + hb];
;             const float mx = fmaxf(l0, fmaxf(l1, l2));
;             float w0 = fexp2(l0 - mx), w1 = fexp2(l1 - mx), w2 = fexp2(l2 - mx);
;             const float iw = frcp(w0 + w1 + w2); w0 *= iw; w1 *= iw; w2 *= iw;
;             const u32x4 a = *(const u32x4*)(OP + ((size_t)0 * MH + r) * 512 + lane * 8), b = *(const u32x4*)(OP + ((size_t)1 * MH + r) * 512 + lane * 8), c = *(const u32x4*)(OP + ((size_t)2 * MH + r) * 512 + lane * 8);
.LBB0_151:
	s_andn2_b64 vcc, exec, s[40:41]
	s_cbranch_vccnz .LBB0_156
	v_ashrrev_i32_e32 v4, 6, v187
	s_lshl_b32 s40, s11, 3
	v_add_u32_e32 v3, s40, v4
	s_movk_i32 s14, 0x4000
	v_cmp_gt_i32_e32 vcc, s14, v3
	s_and_saveexec_b64 s[42:43], vcc
	s_cbranch_execz .LBB0_155
	v_and_b32_e32 v1, 64, v178
	v_xor_b32_e32 v0, 1, v178
	v_add_u32_e32 v1, 64, v1
	v_cmp_lt_i32_e32 vcc, v0, v1
	s_load_dwordx2 s[14:15], s[0:1], 0x68
	v_readlane_b32 s12, v255, 31
	v_cndmask_b32_e32 v0, v178, v0, vcc
	s_waitcnt vmcnt(7)
	v_lshlrev_b32_e32 v16, 2, v0
	v_xor_b32_e32 v0, 2, v178
	v_cmp_lt_i32_e32 vcc, v0, v1
	s_lshl_b32 s48, s12, 7
	s_ashr_i32 s49, s48, 31
	v_cndmask_b32_e32 v0, v178, v0, vcc
	v_lshlrev_b32_e32 v17, 2, v0
	v_xor_b32_e32 v0, 4, v178
	v_cmp_lt_i32_e32 vcc, v0, v1
	s_lshl_b32 s46, s10, 3
	s_lshl_b64 s[48:49], s[48:49], 2
	v_cndmask_b32_e32 v0, v178, v0, vcc
	v_lshlrev_b32_e32 v18, 2, v0
	v_xor_b32_e32 v0, 8, v178
	v_cmp_lt_i32_e32 vcc, v0, v1
	s_waitcnt lgkmcnt(0)
	s_add_u32 s14, s14, s48
	s_addc_u32 s15, s15, s49
	v_cndmask_b32_e32 v0, v178, v0, vcc
	v_lshlrev_b32_e32 v19, 2, v0
	v_lshlrev_b32_e32 v0, 5, v187
	v_ashrrev_i32_e32 v5, 31, v4
	s_ashr_i32 s41, s40, 31
	v_and_b32_e32 v0, 0x1e0, v0
	v_mov_b32_e32 v1, v2
	v_lshl_add_u64 v[4:5], v[4:5], 0, s[40:41]
	v_lshl_add_u64 v[0:1], s[14:15], 0, v[0:1]
	v_mad_u64_u32 v[6:7], s[14:15], v4, s8, 0
	v_mad_i32_i24 v9, v5, s8, v7
	v_lshlrev_b32_e32 v7, 4, v187
	v_and_b32_e32 v14, 0x3f0, v7
	s_waitcnt vmcnt(6)
	v_and_b32_e32 v20, 56, v187
	v_or_b32_e32 v8, v6, v14
	v_mad_u64_u32 v[6:7], s[14:15], v4, s9, 0
	v_lshlrev_b64 v[12:13], 10, v[4:5]
	s_ashr_i32 s47, s46, 31
	v_or_b32_e32 v10, v6, v14
	v_or_b32_e32 v12, v12, v14
	v_lshlrev_b64 v[14:15], 5, v[4:5]
	v_lshrrev_b32_e32 v4, 1, v20
	s_mul_i32 s48, s10, 0xa000
	s_mul_hi_i32 s49, s46, 0x1400
	v_mad_i32_i24 v11, v5, s9, v7
	s_mul_i32 s50, s10, 0x6000
	s_mul_hi_i32 s51, s46, 0xc00
	s_lshl_b64 s[52:53], s[46:47], 10
	v_or_b32_e32 v14, v14, v4
	s_lshl_b64 s[54:55], s[46:47], 5
	s_mov_b64 s[56:57], 0
	v_readlane_b32 s13, v255, 32
	global_load_dwordx4 v[216:219], v[0:1], off offset:16
	global_load_dwordx4 v[220:223], v[0:1], off
	s_waitcnt vmcnt(0)
	v_lshl_add_u64 v[224:225], s[60:61], 0, v[14:15]
	v_lshl_add_u64 v[226:227], s[60:61], 0, v[12:13]
	v_lshl_add_u64 v[228:229], s[60:61], 0, v[8:9]
	v_add_co_u32_e32 v230, vcc, 0x1e800000, v224
	s_nop 1
	v_addc_co_u32_e32 v231, vcc, 0, v225, vcc
	v_add_co_u32_e32 v232, vcc, 0x1e880000, v224
	s_nop 1
	v_addc_co_u32_e32 v233, vcc, 0, v225, vcc
	v_add_co_u32_e32 v234, vcc, 0x1e900000, v224
	s_nop 1
	v_addc_co_u32_e32 v235, vcc, 0, v225, vcc
	global_load_dword v188, v[230:231], off
	global_load_dword v189, v[232:233], off
	global_load_dword v190, v[234:235], off
	v_add_co_u32_e32 v230, vcc, 0x1b800000, v226
	s_nop 1
	v_addc_co_u32_e32 v231, vcc, 0, v227, vcc
	v_add_co_u32_e32 v232, vcc, 0x1c800000, v226
	s_nop 1
	v_addc_co_u32_e32 v233, vcc, 0, v227, vcc
	v_add_co_u32_e32 v234, vcc, 0x1d800000, v226
	s_nop 1
	v_addc_co_u32_e32 v235, vcc, 0, v227, vcc
	global_load_dwordx4 v[192:195], v[230:231], off
	global_load_dwordx4 v[196:199], v[232:233], off
	global_load_dwordx4 v[200:203], v[234:235], off
	v_add_co_u32_e32 v230, vcc, 0xd800000, v228
	s_nop 1
	v_addc_co_u32_e32 v231, vcc, 0, v229, vcc
	v_add_co_u32_e32 v232, vcc, 0xd801000, v228
	s_nop 1
	v_addc_co_u32_e32 v233, vcc, 0, v229, vcc
	global_load_dwordx4 v[204:207], v[230:231], off offset:1024
	global_load_dwordx4 v[208:211], v[230:231], off offset:2048
	global_load_dwordx4 v[212:215], v[232:233], off
.LBB0_154:
	v_lshl_add_u64 v[4:5], s[60:61], 0, v[14:15]
	v_add_co_u32_e32 v6, vcc, 0x1e800000, v4
	v_lshl_add_u64 v[24:25], s[60:61], 0, v[12:13]
	v_addc_co_u32_e32 v7, vcc, 0, v5, vcc
	v_add_co_u32_e32 v6, vcc, 0x1e880000, v4
	s_mov_b32 s14, 0x1b800000
	s_nop 0
	v_addc_co_u32_e32 v7, vcc, 0, v5, vcc
	v_add_co_u32_e32 v4, vcc, 0x1e900000, v4
	s_nop 0
	v_addc_co_u32_e32 v5, vcc, 0, v5, vcc
	v_add_u32_e32 v3, s46, v3
	v_lshl_add_u64 v[12:13], v[12:13], 0, s[52:53]
	v_lshl_add_u64 v[14:15], v[14:15], 0, s[54:55]
	s_waitcnt vmcnt(6)
	v_mov_b32_e32 v20, v188
	v_mov_b32_e32 v6, v189
	v_mov_b32_e32 v4, v190
	v_max3_f32 v5, v20, v6, v4
	v_sub_f32_e32 v7, v20, v5
	v_sub_f32_e32 v6, v6, v5
	v_exp_f32_e32 v29, v7
	v_exp_f32_e32 v28, v6
	v_sub_f32_e32 v4, v4, v5
	v_exp_f32_e32 v4, v4
	v_add_f32_e32 v5, v29, v28
	v_add_f32_e32 v5, v4, v5
	v_rcp_f32_e32 v30, v5
	s_nop 0
	v_mul_f32_e32 v32, v4, v30
	v_add_co_u32_e32 v4, vcc, s14, v24
	s_mov_b32 s14, 0x1c800000
	s_nop 0
	v_addc_co_u32_e32 v5, vcc, 0, v25, vcc
	v_add_co_u32_e32 v20, vcc, s14, v24
	s_mov_b32 s14, 0x1d800000
	s_nop 0
	v_addc_co_u32_e32 v21, vcc, 0, v25, vcc
	s_waitcnt vmcnt(3)
; __device__ __forceinline__ unsigned pk2(float lo, float hi) { f32x2 v = {lo, hi}; bf16x2_t b = __builtin_convertvector(v, bf16x2_t); return __builtin_bit_cast(unsigned, b); }
; __device__ __forceinline__ float bflo(unsigned w) { return __uint_as_float(w << 16); }
; __device__ __forceinline__ float bfhi(unsigned w) { return __uint_as_float(w & 0xffff0000u); }
; __device__ __forceinline__ void post_rows(const bf16_t* OP, const float* LSE, const bf16_t* zC, bf16_t* yb, bf16_t* yc, const float* hnorm, int tid, int bid, int nbk) {
;     ...
;             const u32x4 a = *(const u32x4*)(OP + ((size_t)0 * MH + r) * 512 + lane * 8), b = *(const u32x4*)(OP + ((size_t)1 * MH + r) * 512 + lane * 8), c = *(const u32x4*)(OP + ((size_t)2 * MH + r) * 512 + lane * 8);
;             u32x4 o;
;             o.x = pk2(w0 * bflo(a.x) + w1 * bflo(b.x) + w2 * bflo(c.x), w0 * bfhi(a.x) + w1 * bfhi(b.x) + w2 * bfhi(c.x));
;             o.y = pk2(w0 * bflo(a.y) + w1 * bflo(b.y) + w2 * bflo(c.y), w0 * bfhi(a.y) + w1 * bfhi(b.y) + w2 * bfhi(c.y));
;             o.z = pk2(w0 * bflo(a.z) + w1 * bflo(b.z) + w2 * bflo(c.z), w0 * bfhi(a.z) + w1 * bfhi(b.z) + w2 * bfhi(c.z));
;             o.w = pk2(w0 * bflo(a.w) + w1 * bflo(b.w) + w2 * bflo(c.w), w0 * bfhi(a.w) + w1 * bfhi(b.w) + w2 * bfhi(c.w));
;             *(u32x4*)(yb + (size_t)r * 1536 + lane * 8) = o;
	v_mov_b32_e32 v4, v192
	v_mov_b32_e32 v5, v193
	v_mov_b32_e32 v6, v194
	v_mov_b32_e32 v7, v195
	v_add_co_u32_e32 v24, vcc, s14, v24
	v_mov_b32_e32 v20, v196
	v_mov_b32_e32 v21, v197
	v_mov_b32_e32 v22, v198
	v_mov_b32_e32 v23, v199
	s_nop 0
	v_addc_co_u32_e32 v25, vcc, 0, v25, vcc
	v_mov_b32_e32 v24, v200
	v_mov_b32_e32 v25, v201
	v_mov_b32_e32 v26, v202
	v_mov_b32_e32 v27, v203
	v_pk_mul_f32 v[28:29], v[28:29], v[30:31] op_sel_hi:[1,0]
	s_mov_b32 s14, 0x18800000
	v_lshlrev_b32_e32 v34, 16, v4
	v_and_b32_e32 v31, 0xffff0000, v4
	v_and_b32_e32 v35, 0xffff0000, v20
	v_lshlrev_b32_e32 v30, 16, v20
	v_pk_mul_f32 v[34:35], v[28:29], v[34:35] op_sel:[1,0] op_sel_hi:[0,1]
	v_lshlrev_b32_e32 v36, 16, v24
	v_and_b32_e32 v37, 0xffff0000, v24
	v_pk_fma_f32 v[30:31], v[28:29], v[30:31], v[34:35]
	v_lshlrev_b32_e32 v20, 16, v5
	v_pk_fma_f32 v[30:31], v[32:33], v[36:37], v[30:31] op_sel_hi:[0,1,1]
	v_cvt_pk_bf16_f32 v4, v30, v31
	v_lshlrev_b32_e32 v30, 16, v21
	v_and_b32_e32 v21, 0xffff0000, v21
	v_and_b32_e32 v31, 0xffff0000, v5
	v_pk_mul_f32 v[20:21], v[28:29], v[20:21] op_sel:[1,0] op_sel_hi:[0,1]
	v_lshlrev_b32_e32 v24, 16, v25
	v_and_b32_e32 v25, 0xffff0000, v25
	v_pk_fma_f32 v[20:21], v[28:29], v[30:31], v[20:21]
	v_lshlrev_b32_e32 v30, 16, v26
	v_pk_fma_f32 v[20:21], v[32:33], v[24:25], v[20:21] op_sel_hi:[0,1,1]
	v_lshlrev_b32_e32 v24, 16, v6
	v_and_b32_e32 v25, 0xffff0000, v22
	v_cvt_pk_bf16_f32 v5, v20, v21
	v_lshlrev_b32_e32 v20, 16, v22
	v_and_b32_e32 v21, 0xffff0000, v6
	v_pk_mul_f32 v[24:25], v[28:29], v[24:25] op_sel:[1,0] op_sel_hi:[0,1]
	v_and_b32_e32 v31, 0xffff0000, v26
	v_pk_fma_f32 v[20:21], v[28:29], v[20:21], v[24:25]
	v_lshlrev_b32_e32 v22, 16, v7
	v_pk_fma_f32 v[20:21], v[32:33], v[30:31], v[20:21] op_sel_hi:[0,1,1]
	v_cvt_pk_bf16_f32 v6, v20, v21
	v_lshlrev_b32_e32 v20, 16, v23
	v_and_b32_e32 v23, 0xffff0000, v23
	v_and_b32_e32 v21, 0xffff0000, v7
	v_pk_mul_f32 v[22:23], v[28:29], v[22:23] op_sel:[1,0] op_sel_hi:[0,1]
	v_pk_fma_f32 v[20:21], v[28:29], v[20:21], v[22:23]
	v_lshlrev_b32_e32 v22, 16, v27
	v_and_b32_e32 v23, 0xffff0000, v27
	v_pk_fma_f32 v[20:21], v[32:33], v[22:23], v[20:21] op_sel_hi:[0,1,1]
	v_cvt_pk_bf16_f32 v7, v20, v21
	v_lshl_add_u64 v[20:21], s[60:61], 0, v[10:11]
	v_add_co_u32_e32 v34, vcc, s14, v20
	v_lshl_add_u64 v[24:25], s[60:61], 0, v[8:9]
	s_nop 0
	v_addc_co_u32_e32 v35, vcc, 0, v21, vcc
	s_mov_b32 s14, 0xd800000
	v_add_co_u32_e32 v20, vcc, s14, v24
	s_mov_b32 s14, 0xd801000
	s_nop 0
	v_addc_co_u32_e32 v21, vcc, 0, v25, vcc
	global_store_dwordx4 v[34:35], v[4:7], off offset:1024
	v_add_co_u32_e32 v24, vcc, s14, v24
	s_nop 1
	s_waitcnt vmcnt(1)
; __device__ __forceinline__ unsigned pk2(float lo, float hi) { f32x2 v = {lo, hi}; bf16x2_t b = __builtin_convertvector(v, bf16x2_t); return __builtin_bit_cast(unsigned, b); }
; __device__ __forceinline__ float bflo(unsigned w) { return __uint_as_float(w << 16); }
; __device__ __forceinline__ float bfhi(unsigned w) { return __uint_as_float(w & 0xffff0000u); }
; __device__ __forceinline__ float siluf_(float x) { return x * frcp(1.f + fexp2(-LOG2E * x)); }
; __device__ __forceinline__ void post_rows(const bf16_t* OP, const float* LSE, const bf16_t* zC, bf16_t* yb, bf16_t* yc, const float* hnorm, int tid, int bid, int nbk) {
;     ...
;         {
;             const bf16_t* zr = zC + (size_t)r * 2560 + lane * 8;
;             const u32x4 a = *(const u32x4*)(zr + 512), b = *(const u32x4*)(zr + 1024), g = *(const u32x4*)(zr + 2048);
;             float s[8], og[8];
;             s[0] = bflo(a.x) + bflo(b.x); s[1] = bfhi(a.x) + bfhi(b.x); s[2] = bflo(a.y) + bflo(b.y); s[3] = bfhi(a.y) + bfhi(b.y);
;             s[4] = bflo(a.z) + bflo(b.z); s[5] = bfhi(a.z) + bfhi(b.z); s[6] = bflo(a.w) + bflo(b.w); s[7] = bfhi(a.w) + bfhi(b.w);
;             og[0] = bflo(g.x); og[1] = bfhi(g.x); og[2] = bflo(g.y); og[3] = bfhi(g.y); og[4] = bflo(g.z); og[5] = bfhi(g.z); og[6] = bflo(g.w); og[7] = bfhi(g.w);
;             float ss = 0.f;
; #pragma unroll
;             for (int i = 0; i < 8; ++i) ss += s[i] * s[i];
;             ss += __shfl_xor(ss, 1); ss += __shfl_xor(ss, 2); ss += __shfl_xor(ss, 4); ss += __shfl_xor(ss, 8);
;             const float rn = 1.0f / sqrtf(ss * (1.f / 128.f) + 1e-6f);
;             const float* gn = hnorm + (lane & 15) * 8;
;             float y[8];
; #pragma unroll
;             for (int i = 0; i < 8; ++i) y[i] = s[i] * rn * gn[i] * siluf_(og[i]);
;             u32x4 o; o.x = pk2(y[0], y[1]); o.y = pk2(y[2], y[3]); o.z = pk2(y[4], y[5]); o.w = pk2(y[6], y[7]);
;             *(u32x4*)(yc + (size_t)r * 1536 + lane * 8) = o;
;         }
	v_mov_b32_e32 v4, v204
	v_mov_b32_e32 v5, v205
	v_mov_b32_e32 v6, v206
	v_mov_b32_e32 v7, v207
	s_nop 0
	v_mov_b32_e32 v20, v208
	v_mov_b32_e32 v21, v209
	v_mov_b32_e32 v22, v210
	v_mov_b32_e32 v23, v211
	v_addc_co_u32_e32 v25, vcc, 0, v25, vcc
	v_mov_b32_e32 v24, v212
	v_mov_b32_e32 v25, v213
	v_mov_b32_e32 v26, v214
	v_mov_b32_e32 v27, v215
	v_lshl_add_u64 v[8:9], v[8:9], 0, s[48:49]
	v_lshl_add_u64 v[10:11], v[10:11], 0, s[50:51]
	v_lshl_add_u64 v[224:225], s[60:61], 0, v[14:15]
	v_lshl_add_u64 v[226:227], s[60:61], 0, v[12:13]
	v_lshl_add_u64 v[228:229], s[60:61], 0, v[8:9]
	v_add_co_u32_e32 v230, vcc, 0x1e800000, v224
	s_nop 1
	v_addc_co_u32_e32 v231, vcc, 0, v225, vcc
	v_add_co_u32_e32 v232, vcc, 0x1e880000, v224
	s_nop 1
	v_addc_co_u32_e32 v233, vcc, 0, v225, vcc
	v_add_co_u32_e32 v234, vcc, 0x1e900000, v224
	s_nop 1
	v_addc_co_u32_e32 v235, vcc, 0, v225, vcc
	global_load_dword v188, v[230:231], off
	global_load_dword v189, v[232:233], off
	global_load_dword v190, v[234:235], off
	v_add_co_u32_e32 v230, vcc, 0x1b800000, v226
	s_nop 1
	v_addc_co_u32_e32 v231, vcc, 0, v227, vcc
	v_add_co_u32_e32 v232, vcc, 0x1c800000, v226
	s_nop 1
	v_addc_co_u32_e32 v233, vcc, 0, v227, vcc
	v_add_co_u32_e32 v234, vcc, 0x1d800000, v226
	s_nop 1
	v_addc_co_u32_e32 v235, vcc, 0, v227, vcc
	global_load_dwordx4 v[192:195], v[230:231], off
	global_load_dwordx4 v[196:199], v[232:233], off
	global_load_dwordx4 v[200:203], v[234:235], off
	v_add_co_u32_e32 v230, vcc, 0xd800000, v228
	s_nop 1
	v_addc_co_u32_e32 v231, vcc, 0, v229, vcc
	v_add_co_u32_e32 v232, vcc, 0xd801000, v228
	s_nop 1
	v_addc_co_u32_e32 v233, vcc, 0, v229, vcc
	global_load_dwordx4 v[204:207], v[230:231], off offset:1024
	global_load_dwordx4 v[208:211], v[230:231], off offset:2048
	global_load_dwordx4 v[212:215], v[232:233], off
	v_lshlrev_b32_e32 v28, 16, v7
	v_and_b32_e32 v29, 0xffff0000, v7
	v_lshlrev_b32_e32 v30, 16, v23
	v_and_b32_e32 v31, 0xffff0000, v23
	v_pk_add_f32 v[36:37], v[28:29], v[30:31]
	v_lshlrev_b32_e32 v28, 16, v6
	v_and_b32_e32 v29, 0xffff0000, v6
	v_lshlrev_b32_e32 v6, 16, v22
	v_and_b32_e32 v7, 0xffff0000, v22
	v_lshlrev_b32_e32 v22, 16, v26
	v_and_b32_e32 v23, 0xffff0000, v26
	v_mul_f32_e32 v26, 0xbfb8aa3b, v22
	v_mul_f32_e32 v45, 0xbfb8aa3b, v23
	v_exp_f32_e32 v26, v26
	v_exp_f32_e32 v45, v45
	v_lshlrev_b32_e32 v46, 16, v21
	v_and_b32_e32 v47, 0xffff0000, v21
	v_add_f32_e32 v26, 1.0, v26
	v_add_f32_e32 v45, 1.0, v45
	v_rcp_f32_e32 v44, v26
	v_rcp_f32_e32 v45, v45
	v_lshlrev_b32_e32 v38, 16, v27
	v_and_b32_e32 v39, 0xffff0000, v27
	v_pk_add_f32 v[6:7], v[28:29], v[6:7]
	v_pk_mul_f32 v[22:23], v[44:45], v[22:23]
	v_lshlrev_b32_e32 v44, 16, v5
	v_and_b32_e32 v45, 0xffff0000, v5
	v_pk_add_f32 v[44:45], v[44:45], v[46:47]
	v_lshlrev_b32_e32 v46, 16, v25
	v_mul_f32_e32 v5, 0xbfb8aa3b, v46
	v_mov_b32_e32 v26, v216
	v_mov_b32_e32 v27, v217
	v_mov_b32_e32 v28, v218
	v_mov_b32_e32 v29, v219
	v_mov_b32_e32 v30, v220
	v_mov_b32_e32 v31, v221
	v_mov_b32_e32 v32, v222
	v_mov_b32_e32 v33, v223
	v_exp_f32_e32 v5, v5
	v_and_b32_e32 v47, 0xffff0000, v25
	v_and_b32_e32 v21, 0xffff0000, v24
	v_pk_mul_f32 v[48:49], v[44:45], v[44:45]
	v_add_f32_e32 v5, 1.0, v5
	v_rcp_f32_e32 v50, v5
	v_mul_f32_e32 v5, 0xbfb8aa3b, v47
	v_exp_f32_e32 v5, v5
	v_pk_mul_f32 v[42:43], v[6:7], v[6:7]
	v_pk_mul_f32 v[40:41], v[36:37], v[36:37]
	v_add_f32_e32 v5, 1.0, v5
	v_rcp_f32_e32 v51, v5
	v_and_b32_e32 v5, 0xffff0000, v20
	v_pk_mul_f32 v[46:47], v[50:51], v[46:47]
	v_lshlrev_b32_e32 v50, 16, v4
	v_and_b32_e32 v51, 0xffff0000, v4
	v_lshlrev_b32_e32 v4, 16, v20
	v_pk_add_f32 v[4:5], v[50:51], v[4:5]
	v_lshlrev_b32_e32 v20, 16, v24
	v_pk_mul_f32 v[24:25], v[4:5], v[4:5]
	v_mul_f32_e32 v50, 0xbfb8aa3b, v20
	v_add_f32_e32 v24, v24, v25
	v_add_f32_e32 v24, v48, v24
	v_add_f32_e32 v24, v49, v24
	v_add_f32_e32 v24, v42, v24
	v_add_f32_e32 v24, v43, v24
	v_add_f32_e32 v24, v40, v24
	v_add_f32_e32 v24, v41, v24
	ds_bpermute_b32 v25, v16, v24
	v_mul_f32_e32 v51, 0xbfb8aa3b, v21
	v_exp_f32_e32 v50, v50
	v_exp_f32_e32 v51, v51
	s_waitcnt lgkmcnt(0)
	v_add_f32_e32 v24, v24, v25
	ds_bpermute_b32 v25, v17, v24
	v_add_f32_e32 v50, 1.0, v50
	v_add_f32_e32 v51, 1.0, v51
	v_rcp_f32_e32 v50, v50
	v_rcp_f32_e32 v51, v51
	s_waitcnt lgkmcnt(0)
	v_add_f32_e32 v24, v24, v25
	ds_bpermute_b32 v25, v18, v24
	v_pk_mul_f32 v[20:21], v[50:51], v[20:21]
	s_waitcnt lgkmcnt(0)
	v_add_f32_e32 v24, v24, v25
	ds_bpermute_b32 v25, v19, v24
	s_waitcnt lgkmcnt(0)
	v_add_f32_e32 v24, v24, v25
	v_fmamk_f32 v24, v24, 0x3c000000, v175
	v_cmp_gt_f32_e32 vcc, s33, v24
	v_mul_f32_e32 v25, 0x4f800000, v24
	s_nop 0
	v_cndmask_b32_e32 v24, v24, v25, vcc
	v_sqrt_f32_e32 v25, v24
	s_nop 0
	v_add_u32_e32 v40, -1, v25
	v_fma_f32 v41, -v40, v25, v24
	v_cmp_ge_f32_e64 s[40:41], 0, v41
	v_add_u32_e32 v41, 1, v25
	s_nop 0
	v_cndmask_b32_e64 v40, v25, v40, s[40:41]
	v_fma_f32 v25, -v41, v25, v24
	v_cmp_lt_f32_e64 s[40:41], 0, v25
	s_nop 1
	v_cndmask_b32_e64 v25, v40, v41, s[40:41]
	v_mul_f32_e32 v40, 0x37800000, v25
	v_cndmask_b32_e32 v25, v25, v40, vcc
	v_cmp_class_f32_e32 vcc, v24, v180
	s_nop 1
	v_cndmask_b32_e32 v24, v25, v24, vcc
	v_div_scale_f32 v25, s[14:15], v24, v24, 1.0
	v_rcp_f32_e32 v40, v25
	s_movk_i32 s14, 0x3fff
	v_fma_f32 v41, -v25, v40, 1.0
	v_fmac_f32_e32 v40, v41, v40
	v_div_scale_f32 v41, vcc, 1.0, v24, 1.0
	v_mul_f32_e32 v42, v41, v40
	v_fma_f32 v43, -v25, v42, v41
	v_fmac_f32_e32 v42, v43, v40
	v_fma_f32 v25, -v25, v42, v41
	v_div_fmas_f32 v25, v25, v40, v42
	v_div_fixup_f32 v24, v25, v24, 1.0
	v_pk_mul_f32 v[6:7], v[6:7], v[24:25] op_sel_hi:[1,0]
	v_pk_mul_f32 v[4:5], v[4:5], v[24:25] op_sel_hi:[1,0]
	v_pk_mul_f32 v[6:7], v[26:27], v[6:7]
	v_pk_mul_f32 v[4:5], v[30:31], v[4:5]
	v_pk_mul_f32 v[6:7], v[22:23], v[6:7]
	v_mul_f32_e32 v22, 0xbfb8aa3b, v38
	v_mul_f32_e32 v23, 0xbfb8aa3b, v39
	v_exp_f32_e32 v22, v22
	v_exp_f32_e32 v23, v23
	v_pk_mul_f32 v[4:5], v[20:21], v[4:5]
	v_pk_mul_f32 v[20:21], v[44:45], v[24:25] op_sel_hi:[1,0]
	v_add_f32_e32 v22, 1.0, v22
	v_add_f32_e32 v23, 1.0, v23
	v_rcp_f32_e32 v22, v22
	v_rcp_f32_e32 v23, v23
	v_pk_mul_f32 v[24:25], v[36:37], v[24:25] op_sel_hi:[1,0]
	v_pk_mul_f32 v[20:21], v[32:33], v[20:21]
	v_pk_mul_f32 v[24:25], v[28:29], v[24:25]
	v_pk_mul_f32 v[22:23], v[22:23], v[38:39]
	v_pk_mul_f32 v[20:21], v[46:47], v[20:21]
	v_pk_mul_f32 v[22:23], v[22:23], v[24:25]
	v_cmp_lt_i32_e32 vcc, s14, v3
	v_cvt_pk_bf16_f32 v4, v4, v5
	v_cvt_pk_bf16_f32 v5, v20, v21
	v_cvt_pk_bf16_f32 v6, v6, v7
	v_cvt_pk_bf16_f32 v7, v22, v23
	s_or_b64 s[56:57], vcc, s[56:57]
	global_store_dwordx4 v[34:35], v[4:7], off offset:2048
	s_andn2_b64 exec, exec, s[56:57]
	s_cbranch_execnz .LBB0_154
